# plus: per-unit scheduler bound test trimmed (uniform v_cmp feeds s_cmp_lg_u64 directly, no cndmask/readfirstlane round trip)
# speedup vs baseline: 1.0277x; 1.0006x over previous
;     __device__ bool next(int i, int& pm, int& pn) const {
;         const long L = (long)i * G + c; if (__builtin_amdgcn_readfirstlane((int)(L >= nwg))) return false;
;         int wgid = (int)L; { const int q = nwg / NXCD, r = nwg % NXCD, xcd = wgid % NXCD, off = wgid / NXCD; wgid = (xcd < r ? xcd * (q + 1) : r * (q + 1) + (xcd - r) * q) + off; }
;         const int nig = WGM * nN, gid = wgid / nig, t = wgid - gid * nig, fm = gid * WGM, gsz = (nM - fm) < WGM ? (nM - fm) : WGM;
;         int pm_, pn_;
;         if (gsz == WGM) { pm_ = fm + (t & (WGM - 1)); pn_ = t >> 3; }
;         else { pm_ = fm + t % gsz; pn_ = t / gsz; }
;         pm = __builtin_amdgcn_readfirstlane(pm_); pn = __builtin_amdgcn_readfirstlane(pn_); return true;
;     __device__ __forceinline__ bool next(int i, pg8::Unit& u) const {
;         if (kind == 0) {
;             int pm, pn; if (!o.next(i, pm, pn)) return false;
;             u.A = A + (size_t)pm * 256 * lda; u.B = B + (size_t)pn * 256 * ldb; u.lda = lda; u.ldb = ldb; u.nt = nt; u.pm = pm; u.pn = pn; u.sub = 0; return true;
;         } else if (kind == 1) {
;             const int L = i * o.G + o.c; if (L >= 160) return false;
;             const int l = L / 40, r = L % 40, pm = r >> 2, pn = r & 3;
;             u.A = A + ((size_t)l * 2560 + pm * 256) * 2048; u.B = B + ((size_t)l * WL + OFF_KV) * 2 + (size_t)pn * 256 * 2048;
;             u.lda = 2048; u.ldb = 2048; u.nt = 16; u.pm = l * 10 + pm; u.pn = pn; u.sub = 0; return true;
;         } else {
;             const int tile = i / 6, s = i - tile * 6, br = s >> 1;
;             int pm, pn; if (!o.next(tile, pm, pn)) return false;
.LBB0_148:
	s_mov_b32 s14, s89
	s_add_i32 s89, s89, 1
	s_mov_b64 s[40:41], s[74:75]
	s_mov_b64 s[42:43], s[86:87]
	v_mov_b32_e32 v134, v130
	v_mov_b32_e32 v138, v132
	s_mov_b32 s66, s2
	s_mov_b32 s35, s18
	s_mov_b32 s96, s84
	s_mov_b32 s36, s69
	s_mov_b32 s22, s46
	s_mov_b32 s52, s70
	s_mov_b64 s[28:29], s[74:75]
	s_mov_b64 s[58:59], s[86:87]
	s_mov_b32 s49, s90
	s_mov_b32 s62, s92
	s_mov_b32 s64, s71
	s_mov_b32 s48, s72
	s_mov_b32 s20, s70
	s_mov_b32 s63, s46
	s_mov_b32 s17, s90
	s_mov_b32 s16, s92
	s_mov_b32 s37, s71
	s_mov_b32 s34, s72
	s_cmp_lt_i32 s68, 1
	s_mov_b64 s[2:3], -1
	s_cbranch_scc1 .LBB0_163
	s_cmp_lg_u32 s68, 1
	s_cbranch_scc0 .LBB0_159
	s_mul_hi_u32 s2, s89, 0xaaaaaaab
	s_lshr_b32 s15, s2, 2
	v_readlane_b32 s2, v246, 2
	v_readlane_b32 s3, v246, 3
	s_mov_b32 s6, s2
	s_mul_i32 s3, s15, s6
	v_readlane_b32 s6, v246, 62
	s_mul_hi_i32 s2, s15, s2
	v_readlane_b32 s7, v246, 63
	s_add_u32 s6, s3, s6
	s_addc_u32 s7, s2, s7
	v_readlane_b32 s2, v244, 32
	v_readlane_b32 s3, v244, 33
	s_mov_b64 s[60:61], 0
	s_mov_b64 s[74:75], s[28:29]
	v_mov_b64_e32 v[2:3], s[2:3]
	v_cmp_ge_i64_e32 vcc, s[6:7], v[2:3]
	s_mov_b64 s[86:87], s[58:59]
	s_mov_b32 s90, s49
	s_mov_b32 s92, s62
	s_cmp_lg_u64 vcc, 0
	s_cselect_b64 s[18:19], -1, 0
	s_mov_b64 s[2:3], 0
	s_and_b64 vcc, exec, s[18:19]
	s_mov_b32 s71, s64
	s_mov_b32 s72, s48
	s_mov_b32 s70, s20
	s_mov_b32 s46, s63
	s_cbranch_vccnz .LBB0_159
	s_ashr_i32 s7, s6, 31
	s_lshr_b32 s7, s7, 29
	s_add_i32 s7, s6, s7
	s_ashr_i32 s10, s7, 3
	s_and_b32 s7, s7, -8
	s_sub_i32 s6, s6, s7
	s_lshr_b32 s7, s6, 31
	v_readlane_b32 s4, v244, 55
	s_or_b32 s7, s4, s7
	s_mul_i32 s18, s7, s6
	s_add_i32 s18, s18, s10
	s_abs_i32 s7, s18
	v_readlane_b32 s4, v244, 58
	s_mul_hi_u32 s10, s7, s4
	v_readlane_b32 s46, v244, 42
	s_mul_i32 s11, s10, s46
	s_sub_i32 s7, s7, s11
	s_ashr_i32 s6, s18, 31
	s_add_i32 s11, s10, 1
	s_sub_i32 s19, s7, s46
	s_cmp_ge_u32 s7, s46
	s_cselect_b32 s10, s11, s10
	s_cselect_b32 s7, s19, s7
	s_add_i32 s11, s10, 1
	s_cmp_ge_u32 s7, s46
	s_cselect_b32 s7, s11, s10
	s_xor_b32 s7, s7, s6
	s_sub_i32 s6, s7, s6
	s_mul_i32 s7, s6, s46
	s_lshl_b32 s46, s6, 3
	v_readlane_b32 s4, v244, 43
	s_sub_i32 s19, s18, s7
	s_sub_i32 s60, s4, s46
	s_cmp_lt_i32 s60, 8
	s_mov_b64 s[6:7], -1
	s_cbranch_scc0 .LBB0_153
	s_abs_i32 s6, s60
	v_cvt_f32_u32_e32 v0, s6
	s_sub_i32 s11, 0, s6
	s_abs_i32 s10, s19
	s_xor_b32 s7, s19, s60
	v_rcp_iflag_f32_e32 v0, v0
	s_ashr_i32 s7, s7, 31
	v_mul_f32_e32 v0, 0x4f7ffffe, v0
	v_cvt_u32_f32_e32 v0, v0
	s_nop 0
	v_readfirstlane_b32 s61, v0
	s_mul_i32 s11, s11, s61
	s_mul_hi_u32 s11, s61, s11
	s_add_i32 s61, s61, s11
	s_mul_hi_u32 s11, s10, s61
	s_mul_i32 s61, s11, s6
	s_sub_i32 s10, s10, s61
	s_add_i32 s65, s11, 1
	s_sub_i32 s61, s10, s6
	s_cmp_ge_u32 s10, s6
	s_cselect_b32 s11, s65, s11
	s_cselect_b32 s10, s61, s10
	s_add_i32 s61, s11, 1
	s_cmp_ge_u32 s10, s6
	s_cselect_b32 s6, s61, s11
	s_xor_b32 s6, s6, s7
	s_sub_i32 s70, s6, s7
	s_mul_i32 s6, s70, s60
	s_sub_i32 s6, s19, s6
	s_mov_b32 s65, 0x13fff
	s_add_i32 s72, s6, s46
	s_mov_b64 s[6:7], 0

;     __device__ bool next(int i, int& pm, int& pn) const {
;         const long L = (long)i * G + c; if (__builtin_amdgcn_readfirstlane((int)(L >= nwg))) return false;
;         int wgid = (int)L; { const int q = nwg / NXCD, r = nwg % NXCD, xcd = wgid % NXCD, off = wgid / NXCD; wgid = (xcd < r ? xcd * (q + 1) : r * (q + 1) + (xcd - r) * q) + off; }
;         const int nig = WGM * nN, gid = wgid / nig, t = wgid - gid * nig, fm = gid * WGM, gsz = (nM - fm) < WGM ? (nM - fm) : WGM;
;         int pm_, pn_;
;         if (gsz == WGM) { pm_ = fm + (t & (WGM - 1)); pn_ = t >> 3; }
;         else { pm_ = fm + t % gsz; pn_ = t / gsz; }
;         pm = __builtin_amdgcn_readfirstlane(pm_); pn = __builtin_amdgcn_readfirstlane(pn_); return true;
;     __device__ __forceinline__ bool next(int i, pg8::Unit& u) const {
;         if (kind == 0) {
;             int pm, pn; if (!o.next(i, pm, pn)) return false;
;             u.A = A + (size_t)pm * 256 * lda; u.B = B + (size_t)pn * 256 * ldb; u.lda = lda; u.ldb = ldb; u.nt = nt; u.pm = pm; u.pn = pn; u.sub = 0; return true;
.LBB0_163:
	s_andn2_b64 vcc, exec, s[2:3]
	s_cbranch_vccnz .LBB0_171
	v_readlane_b32 s2, v246, 56
	v_readlane_b32 s6, v246, 2
	s_mul_i32 s2, s89, s2
	v_readlane_b32 s7, v246, 3
	s_mul_hi_u32 s3, s89, s6
	s_add_i32 s3, s3, s2
	s_mul_i32 s2, s89, s6
	v_readlane_b32 s6, v246, 62
	v_readlane_b32 s7, v246, 63
	s_add_u32 s2, s2, s6
	s_addc_u32 s3, s3, s7
	v_readlane_b32 s6, v244, 32
	v_readlane_b32 s7, v244, 33
	s_mov_b64 s[60:61], 0
	s_nop 0
	v_mov_b64_e32 v[2:3], s[6:7]
	v_cmp_ge_i64_e32 vcc, s[2:3], v[2:3]
	s_nop 1
	s_cmp_lg_u64 vcc, 0
	s_cselect_b64 s[6:7], -1, 0
	s_and_b64 vcc, exec, s[6:7]
	s_cbranch_vccnz .LBB0_170
	s_ashr_i32 s3, s2, 31
	s_lshr_b32 s3, s3, 29
	s_add_i32 s3, s2, s3
	s_ashr_i32 s6, s3, 3
	s_and_b32 s3, s3, -8
	s_sub_i32 s2, s2, s3
	s_lshr_b32 s3, s2, 31
	v_readlane_b32 s4, v244, 55
	s_or_b32 s3, s4, s3
	s_mul_i32 s2, s3, s2
	s_add_i32 s6, s2, s6
	s_abs_i32 s3, s6
	v_readlane_b32 s4, v244, 58
	s_mul_hi_u32 s7, s3, s4
	v_readlane_b32 s14, v244, 42
	s_mul_i32 s10, s7, s14
	s_sub_i32 s3, s3, s10
	s_ashr_i32 s2, s6, 31
	s_add_i32 s10, s7, 1
	s_sub_i32 s11, s3, s14
	s_cmp_ge_u32 s3, s14
	s_cselect_b32 s7, s10, s7
	s_cselect_b32 s3, s11, s3
	s_add_i32 s10, s7, 1
	s_cmp_ge_u32 s3, s14
	s_cselect_b32 s3, s10, s7
	s_xor_b32 s3, s3, s2
	s_sub_i32 s2, s3, s2
	s_mul_i32 s3, s2, s14
	s_lshl_b32 s14, s2, 3
	v_readlane_b32 s2, v244, 43
	s_sub_i32 s7, s6, s3
	s_sub_i32 s15, s2, s14
	s_cmp_lt_i32 s15, 8
	s_mov_b64 s[2:3], -1
	s_cbranch_scc0 .LBB0_167
	s_abs_i32 s2, s15
	v_cvt_f32_u32_e32 v0, s2
	s_sub_i32 s11, 0, s2
	s_abs_i32 s10, s7
	s_xor_b32 s3, s7, s15
	v_rcp_iflag_f32_e32 v0, v0
	s_ashr_i32 s3, s3, 31
	v_mul_f32_e32 v0, 0x4f7ffffe, v0
	v_cvt_u32_f32_e32 v0, v0
	s_nop 0
	v_readfirstlane_b32 s18, v0
	s_mul_i32 s11, s11, s18
	s_mul_hi_u32 s11, s18, s11
	s_add_i32 s18, s18, s11
	s_mul_hi_u32 s11, s10, s18
	s_mul_i32 s18, s11, s2
	s_sub_i32 s10, s10, s18
	s_add_i32 s19, s11, 1
	s_sub_i32 s18, s10, s2
	s_cmp_ge_u32 s10, s2
	s_cselect_b32 s11, s19, s11
	s_cselect_b32 s10, s18, s10
	s_add_i32 s18, s11, 1
	s_cmp_ge_u32 s10, s2
	s_cselect_b32 s2, s18, s11
	s_xor_b32 s2, s2, s3
	s_sub_i32 s20, s2, s3
	s_mul_i32 s2, s20, s15
	s_sub_i32 s2, s7, s2
	s_add_i32 s48, s2, s14
	s_mov_b64 s[2:3], 0
